# adds V-fragment prefetch (spare VGPRs v198-v229) in both diff-attention passes to the combined version
# baseline (speedup 1.0000x reference)
; DI unsigned pack2(float a, float b) { f2_t v = {a, b}; bf2_t r = __builtin_convertvector(v, bf2_t); return __builtin_bit_cast(unsigned, r); }
; DI f32x16 mfma(bf16x8 a, bf16x8 b, f32x16 c) { return __builtin_amdgcn_mfma_f32_32x32x16_bf16(a, b, c, 0, 0, 0); }
; template <int DQK, int DV, bool BIAS>
; DI void attn_tile(const char* cur, const bf16x8* qf, f32x16* o, float& m, float& lsum, int kt, int l32, int hh,
;                   const int* __restrict__ posb, int qpos, int qmin, const int* __restrict__ kpmax, const float* lut) {
;     ...
;       const float sh = m - cb;
;       float rs = 0.f;
; #pragma unroll
;       for (int i = 0; i < 16; ++i) { s0[i] = __builtin_amdgcn_exp2f(s0[i] - sh); rs += s0[i]; }
; #pragma unroll
;       for (int i = 0; i < 16; ++i) { s1[i] = __builtin_amdgcn_exp2f(s1[i] - sh); rs += s1[i]; }
;       lsum += rs;
;       bf16x8 pf[4];
; #pragma unroll
;       for (int ks = 0; ks < 4; ++ks) {
;         const f32x16& sv = (ks < 2) ? s0 : s1;
;         const int b0 = (ks & 1) * 8;
;         uint4 u;
;         u.x = pack2(sv[b0 + 0], sv[b0 + 1]); u.y = pack2(sv[b0 + 2], sv[b0 + 3]);
;         u.z = pack2(sv[b0 + 4], sv[b0 + 5]); u.w = pack2(sv[b0 + 6], sv[b0 + 7]);
;         pf[ks] = __builtin_bit_cast(bf16x8, u);
;       }
; #pragma unroll
;       for (int vb = 0; vb < DV / 32; ++vb)
; #pragma unroll
;         for (int ks = 0; ks < 4; ++ks) {
;           const bf16x8 a = *(const bf16x8*)(cur + KB + (vb * 32 + l32) * VROW + ks * 32 + hh * 16);
;           o[vb] = mfma(a, pf[ks], o[vb]);
;         }
.LBB0_98:
	v_sub_f32_e32 v146, v163, v162
	v_sub_f32_e32 v82, v82, v146
	v_exp_f32_e32 v82, v82
	v_sub_f32_e32 v83, v83, v146
	v_exp_f32_e32 v83, v83
	v_sub_f32_e32 v84, v84, v146
	v_exp_f32_e32 v84, v84
	v_sub_f32_e32 v85, v85, v146
	v_exp_f32_e32 v85, v85
	v_sub_f32_e32 v86, v86, v146
	v_add_f32_e32 v162, 0, v82
	v_exp_f32_e32 v86, v86
	v_sub_f32_e32 v87, v87, v146
	v_add_f32_e32 v162, v83, v162
	v_exp_f32_e32 v87, v87
	v_sub_f32_e32 v88, v88, v146
	v_add_f32_e32 v162, v84, v162
	v_exp_f32_e32 v88, v88
	v_sub_f32_e32 v89, v89, v146
	v_add_f32_e32 v162, v85, v162
	v_exp_f32_e32 v89, v89
	v_sub_f32_e32 v90, v90, v146
	v_add_f32_e32 v162, v86, v162
	v_exp_f32_e32 v90, v90
	v_sub_f32_e32 v91, v91, v146
	v_add_f32_e32 v162, v87, v162
	v_exp_f32_e32 v91, v91
	v_sub_f32_e32 v92, v92, v146
	v_add_f32_e32 v162, v88, v162
	v_exp_f32_e32 v92, v92
	v_sub_f32_e32 v93, v93, v146
	v_add_f32_e32 v162, v89, v162
	v_exp_f32_e32 v93, v93
	v_sub_f32_e32 v94, v94, v146
	v_add_f32_e32 v162, v90, v162
	v_exp_f32_e32 v94, v94
	v_sub_f32_e32 v95, v95, v146
	v_add_f32_e32 v162, v91, v162
	v_exp_f32_e32 v95, v95
	v_sub_f32_e32 v96, v96, v146
	v_add_f32_e32 v162, v92, v162
	v_exp_f32_e32 v96, v96
	v_sub_f32_e32 v97, v97, v146
	v_add_f32_e32 v162, v93, v162
	v_exp_f32_e32 v97, v97
	v_sub_f32_e32 v66, v66, v146
	v_add_f32_e32 v162, v94, v162
	v_exp_f32_e32 v66, v66
	v_sub_f32_e32 v67, v67, v146
	v_add_f32_e32 v162, v95, v162
	v_exp_f32_e32 v67, v67
	v_sub_f32_e32 v68, v68, v146
	v_add_f32_e32 v162, v96, v162
	v_exp_f32_e32 v68, v68
	v_sub_f32_e32 v69, v69, v146
	v_add_f32_e32 v162, v97, v162
	v_exp_f32_e32 v69, v69
	v_sub_f32_e32 v70, v70, v146
	v_add_f32_e32 v162, v66, v162
	v_exp_f32_e32 v164, v70
	v_add_f32_e32 v162, v67, v162
	v_add_f32_e32 v162, v68, v162
	v_add_f32_e32 v162, v69, v162
	v_sub_f32_e32 v71, v71, v146
	v_add_f32_e32 v70, v164, v162
	v_exp_f32_e32 v162, v71
	v_sub_f32_e32 v71, v72, v146
	v_exp_f32_e32 v165, v71
	v_sub_f32_e32 v71, v73, v146
	v_exp_f32_e32 v73, v71
	v_sub_f32_e32 v71, v74, v146
	v_exp_f32_e32 v171, v71
	v_sub_f32_e32 v71, v75, v146
	v_exp_f32_e32 v172, v71
	v_sub_f32_e32 v71, v76, v146
	v_exp_f32_e32 v173, v71
	v_sub_f32_e32 v71, v77, v146
	v_exp_f32_e32 v174, v71
	v_sub_f32_e32 v71, v78, v146
	v_exp_f32_e32 v175, v71
	v_sub_f32_e32 v71, v79, v146
	v_exp_f32_e32 v176, v71
	v_sub_f32_e32 v71, v80, v146
	v_cvt_pk_bf16_f32 v74, v90, v91
	v_add3_u32 v90, s70, v158, v170
	ds_read_b128 v[198:201], v90 offset:13824
	ds_read_b128 v[202:205], v90 offset:13856
	ds_read_b128 v[206:209], v90 offset:13888
	ds_read_b128 v[210:213], v90 offset:13920
	ds_read_b128 v[214:217], v90 offset:18432
	ds_read_b128 v[218:221], v90 offset:18464
	ds_read_b128 v[222:225], v90 offset:18496
	ds_read_b128 v[226:229], v90 offset:18528
	v_exp_f32_e32 v177, v71
	v_sub_f32_e32 v71, v81, v146
	v_cvt_pk_bf16_f32 v78, v82, v83
	v_cvt_pk_bf16_f32 v79, v84, v85
	v_cvt_pk_bf16_f32 v80, v86, v87
	v_cvt_pk_bf16_f32 v81, v88, v89
	ds_read_b128 v[82:85], v90 offset:9216
	ds_read_b128 v[86:89], v90 offset:9248
	s_waitcnt lgkmcnt(1)
	v_mfma_f32_32x32x16_bf16 v[2:17], v[82:85], v[78:81], v[2:17]
	v_add_f32_e32 v70, v162, v70
	v_add_f32_e32 v70, v165, v70
	v_add_f32_e32 v70, v73, v70
	v_add_f32_e32 v70, v171, v70
	v_cvt_pk_bf16_f32 v75, v92, v93
	v_cvt_pk_bf16_f32 v76, v94, v95
	v_cvt_pk_bf16_f32 v77, v96, v97
	ds_read_b128 v[82:85], v90 offset:9280
	v_add_f32_e32 v70, v172, v70
	s_waitcnt lgkmcnt(1)
	v_mfma_f32_32x32x16_bf16 v[2:17], v[86:89], v[74:77], v[2:17]
	v_add_f32_e32 v70, v173, v70
	v_add_f32_e32 v70, v174, v70
	v_exp_f32_e32 v146, v71
	v_add_f32_e32 v70, v175, v70
	v_add_f32_e32 v70, v176, v70
	v_add_f32_e32 v70, v177, v70
	v_add_f32_e32 v70, v146, v70
	v_add_f32_e32 v159, v159, v70
	v_cvt_pk_bf16_f32 v70, v66, v67
	v_cvt_pk_bf16_f32 v71, v68, v69
	v_cvt_pk_bf16_f32 v72, v164, v162
	v_cvt_pk_bf16_f32 v73, v165, v73
	v_cvt_pk_bf16_f32 v66, v171, v172
	v_cvt_pk_bf16_f32 v67, v173, v174
	s_waitcnt lgkmcnt(0)
	v_mfma_f32_32x32x16_bf16 v[2:17], v[82:85], v[70:73], v[2:17]
	ds_read_b128 v[82:85], v90 offset:9312
	v_cvt_pk_bf16_f32 v68, v175, v176
	v_cvt_pk_bf16_f32 v69, v177, v146
	s_waitcnt lgkmcnt(0)
	s_nop 0
	v_mfma_f32_32x32x16_bf16 v[2:17], v[82:85], v[66:69], v[2:17]
	s_waitcnt lgkmcnt(0)
	v_mfma_f32_32x32x16_bf16 v[18:33], v[198:201], v[78:81], v[18:33]
	v_mfma_f32_32x32x16_bf16 v[18:33], v[202:205], v[74:77], v[18:33]
	v_mfma_f32_32x32x16_bf16 v[18:33], v[206:209], v[70:73], v[18:33]
	v_mfma_f32_32x32x16_bf16 v[18:33], v[210:213], v[66:69], v[18:33]
	ds_read_b128 v[198:201], v90 offset:23040
	ds_read_b128 v[202:205], v90 offset:23072
	ds_read_b128 v[206:209], v90 offset:23104
	ds_read_b128 v[210:213], v90 offset:23136
	v_mfma_f32_32x32x16_bf16 v[34:49], v[214:217], v[78:81], v[34:49]
	v_mfma_f32_32x32x16_bf16 v[34:49], v[218:221], v[74:77], v[34:49]
	v_mfma_f32_32x32x16_bf16 v[34:49], v[222:225], v[70:73], v[34:49]
	v_mfma_f32_32x32x16_bf16 v[34:49], v[226:229], v[66:69], v[34:49]
	s_waitcnt lgkmcnt(0)
	v_mfma_f32_32x32x16_bf16 v[50:65], v[198:201], v[78:81], v[50:65]
	v_mfma_f32_32x32x16_bf16 v[50:65], v[202:205], v[74:77], v[50:65]
	v_mfma_f32_32x32x16_bf16 v[50:65], v[206:209], v[70:73], v[50:65]
	v_mfma_f32_32x32x16_bf16 v[50:65], v[210:213], v[66:69], v[50:65]

; DI unsigned pack2(float a, float b) { f2_t v = {a, b}; bf2_t r = __builtin_convertvector(v, bf2_t); return __builtin_bit_cast(unsigned, r); }
; DI f32x16 mfma(bf16x8 a, bf16x8 b, f32x16 c) { return __builtin_amdgcn_mfma_f32_32x32x16_bf16(a, b, c, 0, 0, 0); }
; template <int DQK, int DV, bool BIAS>
; DI void attn_tile(const char* cur, const bf16x8* qf, f32x16* o, float& m, float& lsum, int kt, int l32, int hh,
;                   const int* __restrict__ posb, int qpos, int qmin, const int* __restrict__ kpmax, const float* lut) {
;     ...
;       const float sh = m - cb;
;       float rs = 0.f;
; #pragma unroll
;       for (int i = 0; i < 16; ++i) { s0[i] = __builtin_amdgcn_exp2f(s0[i] - sh); rs += s0[i]; }
; #pragma unroll
;       for (int i = 0; i < 16; ++i) { s1[i] = __builtin_amdgcn_exp2f(s1[i] - sh); rs += s1[i]; }
;       lsum += rs;
;       bf16x8 pf[4];
; #pragma unroll
;       for (int ks = 0; ks < 4; ++ks) {
;         const f32x16& sv = (ks < 2) ? s0 : s1;
;         const int b0 = (ks & 1) * 8;
;         uint4 u;
;         u.x = pack2(sv[b0 + 0], sv[b0 + 1]); u.y = pack2(sv[b0 + 2], sv[b0 + 3]);
;         u.z = pack2(sv[b0 + 4], sv[b0 + 5]); u.w = pack2(sv[b0 + 6], sv[b0 + 7]);
;         pf[ks] = __builtin_bit_cast(bf16x8, u);
;       }
; #pragma unroll
;       for (int vb = 0; vb < DV / 32; ++vb)
; #pragma unroll
;         for (int ks = 0; ks < 4; ++ks) {
;           const bf16x8 a = *(const bf16x8*)(cur + KB + (vb * 32 + l32) * VROW + ks * 32 + hh * 16);
;           o[vb] = mfma(a, pf[ks], o[vb]);
;         }
.LBB0_111:
	v_sub_f32_e32 v146, v165, v164
	v_sub_f32_e32 v82, v82, v146
	v_exp_f32_e32 v82, v82
	v_sub_f32_e32 v83, v83, v146
	v_exp_f32_e32 v83, v83
	v_sub_f32_e32 v84, v84, v146
	v_exp_f32_e32 v84, v84
	v_sub_f32_e32 v85, v85, v146
	v_exp_f32_e32 v85, v85
	v_sub_f32_e32 v86, v86, v146
	v_add_f32_e32 v164, 0, v82
	v_exp_f32_e32 v86, v86
	v_sub_f32_e32 v87, v87, v146
	v_add_f32_e32 v164, v83, v164
	v_exp_f32_e32 v87, v87
	v_sub_f32_e32 v88, v88, v146
	v_add_f32_e32 v164, v84, v164
	v_exp_f32_e32 v88, v88
	v_sub_f32_e32 v89, v89, v146
	v_add_f32_e32 v164, v85, v164
	v_exp_f32_e32 v89, v89
	v_sub_f32_e32 v90, v90, v146
	v_add_f32_e32 v164, v86, v164
	v_exp_f32_e32 v90, v90
	v_sub_f32_e32 v91, v91, v146
	v_add_f32_e32 v164, v87, v164
	v_exp_f32_e32 v91, v91
	v_sub_f32_e32 v92, v92, v146
	v_add_f32_e32 v164, v88, v164
	v_exp_f32_e32 v92, v92
	v_sub_f32_e32 v93, v93, v146
	v_add_f32_e32 v164, v89, v164
	v_exp_f32_e32 v93, v93
	v_sub_f32_e32 v94, v94, v146
	v_add_f32_e32 v164, v90, v164
	v_exp_f32_e32 v94, v94
	v_sub_f32_e32 v95, v95, v146
	v_add_f32_e32 v164, v91, v164
	v_exp_f32_e32 v95, v95
	v_sub_f32_e32 v96, v96, v146
	v_add_f32_e32 v164, v92, v164
	v_exp_f32_e32 v96, v96
	v_sub_f32_e32 v97, v97, v146
	v_add_f32_e32 v164, v93, v164
	v_exp_f32_e32 v97, v97
	v_sub_f32_e32 v66, v66, v146
	v_add_f32_e32 v164, v94, v164
	v_exp_f32_e32 v66, v66
	v_sub_f32_e32 v67, v67, v146
	v_add_f32_e32 v164, v95, v164
	v_exp_f32_e32 v67, v67
	v_sub_f32_e32 v68, v68, v146
	v_add_f32_e32 v164, v96, v164
	v_exp_f32_e32 v68, v68
	v_sub_f32_e32 v69, v69, v146
	v_add_f32_e32 v164, v97, v164
	v_exp_f32_e32 v69, v69
	v_sub_f32_e32 v70, v70, v146
	v_add_f32_e32 v164, v66, v164
	v_exp_f32_e32 v166, v70
	v_add_f32_e32 v164, v67, v164
	v_add_f32_e32 v164, v68, v164
	v_add_f32_e32 v164, v69, v164
	v_sub_f32_e32 v71, v71, v146
	v_add_f32_e32 v70, v166, v164
	v_exp_f32_e32 v164, v71
	v_sub_f32_e32 v71, v72, v146
	v_exp_f32_e32 v167, v71
	v_sub_f32_e32 v71, v73, v146
	v_exp_f32_e32 v73, v71
	v_sub_f32_e32 v71, v74, v146
	v_exp_f32_e32 v171, v71
	v_sub_f32_e32 v71, v75, v146
	v_exp_f32_e32 v172, v71
	v_sub_f32_e32 v71, v76, v146
	v_exp_f32_e32 v173, v71
	v_sub_f32_e32 v71, v77, v146
	v_exp_f32_e32 v174, v71
	v_sub_f32_e32 v71, v78, v146
	v_exp_f32_e32 v175, v71
	v_sub_f32_e32 v71, v79, v146
	v_exp_f32_e32 v176, v71
	v_sub_f32_e32 v71, v80, v146
	v_cvt_pk_bf16_f32 v74, v90, v91
	v_add3_u32 v90, s47, v160, v170
	ds_read_b128 v[198:201], v90 offset:13824
	ds_read_b128 v[202:205], v90 offset:13856
	ds_read_b128 v[206:209], v90 offset:13888
	ds_read_b128 v[210:213], v90 offset:13920
	ds_read_b128 v[214:217], v90 offset:18432
	ds_read_b128 v[218:221], v90 offset:18464
	ds_read_b128 v[222:225], v90 offset:18496
	ds_read_b128 v[226:229], v90 offset:18528
	v_exp_f32_e32 v177, v71
	v_sub_f32_e32 v71, v81, v146
	v_cvt_pk_bf16_f32 v78, v82, v83
	v_cvt_pk_bf16_f32 v79, v84, v85
	v_cvt_pk_bf16_f32 v80, v86, v87
	v_cvt_pk_bf16_f32 v81, v88, v89
	ds_read_b128 v[82:85], v90 offset:9216
	ds_read_b128 v[86:89], v90 offset:9248
	s_waitcnt lgkmcnt(1)
	v_mfma_f32_32x32x16_bf16 v[50:65], v[82:85], v[78:81], v[50:65]
	v_add_f32_e32 v70, v164, v70
	v_add_f32_e32 v70, v167, v70
	v_add_f32_e32 v70, v73, v70
	v_add_f32_e32 v70, v171, v70
	v_cvt_pk_bf16_f32 v75, v92, v93
	v_cvt_pk_bf16_f32 v76, v94, v95
	v_cvt_pk_bf16_f32 v77, v96, v97
	ds_read_b128 v[82:85], v90 offset:9280
	v_add_f32_e32 v70, v172, v70
	s_waitcnt lgkmcnt(1)
	v_mfma_f32_32x32x16_bf16 v[50:65], v[86:89], v[74:77], v[50:65]
	v_add_f32_e32 v70, v173, v70
	v_add_f32_e32 v70, v174, v70
	v_exp_f32_e32 v146, v71
	v_add_f32_e32 v70, v175, v70
	v_add_f32_e32 v70, v176, v70
	v_add_f32_e32 v70, v177, v70
	v_add_f32_e32 v70, v146, v70
	v_add_f32_e32 v161, v161, v70
	v_cvt_pk_bf16_f32 v70, v66, v67
	v_cvt_pk_bf16_f32 v71, v68, v69
	v_cvt_pk_bf16_f32 v72, v166, v164
	v_cvt_pk_bf16_f32 v73, v167, v73
	v_cvt_pk_bf16_f32 v66, v171, v172
	v_cvt_pk_bf16_f32 v67, v173, v174
	s_waitcnt lgkmcnt(0)
	v_mfma_f32_32x32x16_bf16 v[50:65], v[82:85], v[70:73], v[50:65]
	ds_read_b128 v[82:85], v90 offset:9312
	v_cvt_pk_bf16_f32 v68, v175, v176
	v_cvt_pk_bf16_f32 v69, v177, v146
	s_waitcnt lgkmcnt(0)
	s_nop 0
	v_mfma_f32_32x32x16_bf16 v[50:65], v[82:85], v[66:69], v[50:65]
	s_waitcnt lgkmcnt(0)
	v_mfma_f32_32x32x16_bf16 v[34:49], v[198:201], v[78:81], v[34:49]
	v_mfma_f32_32x32x16_bf16 v[34:49], v[202:205], v[74:77], v[34:49]
	v_mfma_f32_32x32x16_bf16 v[34:49], v[206:209], v[70:73], v[34:49]
	v_mfma_f32_32x32x16_bf16 v[34:49], v[210:213], v[66:69], v[34:49]
	ds_read_b128 v[198:201], v90 offset:23040
	ds_read_b128 v[202:205], v90 offset:23072
	ds_read_b128 v[206:209], v90 offset:23104
	ds_read_b128 v[210:213], v90 offset:23136
	v_mfma_f32_32x32x16_bf16 v[18:33], v[214:217], v[78:81], v[18:33]
	v_mfma_f32_32x32x16_bf16 v[18:33], v[218:221], v[74:77], v[18:33]
	v_mfma_f32_32x32x16_bf16 v[18:33], v[222:225], v[70:73], v[18:33]
	v_mfma_f32_32x32x16_bf16 v[18:33], v[226:229], v[66:69], v[18:33]
	s_waitcnt lgkmcnt(0)
	v_mfma_f32_32x32x16_bf16 v[2:17], v[198:201], v[78:81], v[2:17]
	v_mfma_f32_32x32x16_bf16 v[2:17], v[202:205], v[74:77], v[2:17]
	v_mfma_f32_32x32x16_bf16 v[2:17], v[206:209], v[70:73], v[2:17]
	v_mfma_f32_32x32x16_bf16 v[2:17], v[210:213], v[66:69], v[2:17]
